# FFN-up swiglu epilogue software-pipelined 8 elements per store (no trans wait-state nops, one 64-bit mad)
# baseline (speedup 1.0000x reference)
.LBB0_1578:
	s_andn2_b64 vcc, exec, s[4:5]
	s_mov_b64 s[60:61], 0x9400300
	v_lshl_or_b32 v144, s25, 7, v148
	v_lshl_add_u32 v150, s24, 8, v146
	v_ashrrev_i32_e32 v145, 31, v144
	v_mov_b64_e32 v[142:143], s[12:13]
	s_movk_i32 s17, 0x1600
	v_mad_i64_i32 v[152:153], s[24:25], v150, s17, v[142:143]
	v_lshlrev_b64 v[144:145], 1, v[144:145]
	v_lshl_add_u64 v[152:153], v[152:153], 0, v[144:145]
	v_mul_f32_e32 v160, 0xbfb8aa3b, v128
	v_mul_f32_e32 v161, 0xbfb8aa3b, v129
	v_mul_f32_e32 v162, 0xbfb8aa3b, v130
	v_mul_f32_e32 v163, 0xbfb8aa3b, v131
	v_mul_f32_e32 v164, 0xbfb8aa3b, v120
	v_mul_f32_e32 v165, 0xbfb8aa3b, v121
	v_mul_f32_e32 v166, 0xbfb8aa3b, v122
	v_mul_f32_e32 v167, 0xbfb8aa3b, v123
	v_exp_f32_e32 v160, v160
	v_exp_f32_e32 v161, v161
	v_exp_f32_e32 v162, v162
	v_exp_f32_e32 v163, v163
	v_exp_f32_e32 v164, v164
	v_exp_f32_e32 v165, v165
	v_exp_f32_e32 v166, v166
	v_exp_f32_e32 v167, v167
	v_add_f32_e32 v160, 1.0, v160
	v_add_f32_e32 v161, 1.0, v161
	v_add_f32_e32 v162, 1.0, v162
	v_add_f32_e32 v163, 1.0, v163
	v_add_f32_e32 v164, 1.0, v164
	v_add_f32_e32 v165, 1.0, v165
	v_add_f32_e32 v166, 1.0, v166
	v_add_f32_e32 v167, 1.0, v167
	v_rcp_f32_e32 v160, v160
	v_rcp_f32_e32 v161, v161
	v_rcp_f32_e32 v162, v162
	v_rcp_f32_e32 v163, v163
	v_rcp_f32_e32 v164, v164
	v_rcp_f32_e32 v165, v165
	v_rcp_f32_e32 v166, v166
	v_rcp_f32_e32 v167, v167
	v_mul_f32_e32 v160, v128, v160
	v_mul_f32_e32 v161, v129, v161
	v_mul_f32_e32 v162, v130, v162
	v_mul_f32_e32 v163, v131, v163
	v_mul_f32_e32 v164, v120, v164
	v_mul_f32_e32 v165, v121, v165
	v_mul_f32_e32 v166, v122, v166
	v_mul_f32_e32 v167, v123, v167
	v_mul_f32_e32 v160, v160, v124
	v_mul_f32_e32 v161, v161, v125
	v_mul_f32_e32 v162, v162, v126
	v_mul_f32_e32 v163, v163, v127
	v_mul_f32_e32 v164, v164, v116
	v_mul_f32_e32 v165, v165, v117
	v_mul_f32_e32 v166, v166, v118
	v_mul_f32_e32 v167, v167, v119
	v_cvt_pk_bf16_f32 v176, v160, v161
	v_cvt_pk_bf16_f32 v177, v162, v163
	v_cvt_pk_bf16_f32 v178, v164, v165
	v_cvt_pk_bf16_f32 v179, v166, v167
	global_store_dwordx4 v[152:153], v[176:179], off
	v_mul_f32_e32 v160, 0xbfb8aa3b, v112
	v_mul_f32_e32 v161, 0xbfb8aa3b, v113
	v_mul_f32_e32 v162, 0xbfb8aa3b, v114
	v_mul_f32_e32 v163, 0xbfb8aa3b, v115
	v_mul_f32_e32 v164, 0xbfb8aa3b, v104
	v_mul_f32_e32 v165, 0xbfb8aa3b, v105
	v_mul_f32_e32 v166, 0xbfb8aa3b, v106
	v_mul_f32_e32 v167, 0xbfb8aa3b, v107
	s_mov_b64 s[24:25], 0x16000
	v_exp_f32_e32 v160, v160
	v_exp_f32_e32 v161, v161
	v_exp_f32_e32 v162, v162
	v_exp_f32_e32 v163, v163
	v_exp_f32_e32 v164, v164
	v_exp_f32_e32 v165, v165
	v_exp_f32_e32 v166, v166
	v_exp_f32_e32 v167, v167
	v_lshl_add_u64 v[186:187], v[152:153], 0, s[24:25]
	v_add_f32_e32 v160, 1.0, v160
	v_add_f32_e32 v161, 1.0, v161
	v_add_f32_e32 v162, 1.0, v162
	v_add_f32_e32 v163, 1.0, v163
	v_add_f32_e32 v164, 1.0, v164
	v_add_f32_e32 v165, 1.0, v165
	v_add_f32_e32 v166, 1.0, v166
	v_add_f32_e32 v167, 1.0, v167
	v_rcp_f32_e32 v160, v160
	v_rcp_f32_e32 v161, v161
	v_rcp_f32_e32 v162, v162
	v_rcp_f32_e32 v163, v163
	v_rcp_f32_e32 v164, v164
	v_rcp_f32_e32 v165, v165
	v_rcp_f32_e32 v166, v166
	v_rcp_f32_e32 v167, v167
	v_mul_f32_e32 v160, v112, v160
	v_mul_f32_e32 v161, v113, v161
	v_mul_f32_e32 v162, v114, v162
	v_mul_f32_e32 v163, v115, v163
	v_mul_f32_e32 v164, v104, v164
	v_mul_f32_e32 v165, v105, v165
	v_mul_f32_e32 v166, v106, v166
	v_mul_f32_e32 v167, v107, v167
	v_mul_f32_e32 v160, v160, v108
	v_mul_f32_e32 v161, v161, v109
	v_mul_f32_e32 v162, v162, v110
	v_mul_f32_e32 v163, v163, v111
	v_mul_f32_e32 v164, v164, v100
	v_mul_f32_e32 v165, v165, v101
	v_mul_f32_e32 v166, v166, v102
	v_mul_f32_e32 v167, v167, v103
	v_cvt_pk_bf16_f32 v180, v160, v161
	v_cvt_pk_bf16_f32 v181, v162, v163
	v_cvt_pk_bf16_f32 v182, v164, v165
	v_cvt_pk_bf16_f32 v183, v166, v167
	global_store_dwordx4 v[186:187], v[180:183], off
	v_mul_f32_e32 v160, 0xbfb8aa3b, v96
	v_mul_f32_e32 v161, 0xbfb8aa3b, v97
	v_mul_f32_e32 v162, 0xbfb8aa3b, v98
	v_mul_f32_e32 v163, 0xbfb8aa3b, v99
	v_mul_f32_e32 v164, 0xbfb8aa3b, v88
	v_mul_f32_e32 v165, 0xbfb8aa3b, v89
	v_mul_f32_e32 v166, 0xbfb8aa3b, v90
	v_mul_f32_e32 v167, 0xbfb8aa3b, v91
	s_mov_b64 s[24:25], 0x2c000
	v_exp_f32_e32 v160, v160
	v_exp_f32_e32 v161, v161
	v_exp_f32_e32 v162, v162
	v_exp_f32_e32 v163, v163
	v_exp_f32_e32 v164, v164
	v_exp_f32_e32 v165, v165
	v_exp_f32_e32 v166, v166
	v_exp_f32_e32 v167, v167
	v_lshl_add_u64 v[184:185], v[152:153], 0, s[24:25]
	v_add_f32_e32 v160, 1.0, v160
	v_add_f32_e32 v161, 1.0, v161
	v_add_f32_e32 v162, 1.0, v162
	v_add_f32_e32 v163, 1.0, v163
	v_add_f32_e32 v164, 1.0, v164
	v_add_f32_e32 v165, 1.0, v165
	v_add_f32_e32 v166, 1.0, v166
	v_add_f32_e32 v167, 1.0, v167
	v_rcp_f32_e32 v160, v160
	v_rcp_f32_e32 v161, v161
	v_rcp_f32_e32 v162, v162
	v_rcp_f32_e32 v163, v163
	v_rcp_f32_e32 v164, v164
	v_rcp_f32_e32 v165, v165
	v_rcp_f32_e32 v166, v166
	v_rcp_f32_e32 v167, v167
	v_mul_f32_e32 v160, v96, v160
	v_mul_f32_e32 v161, v97, v161
	v_mul_f32_e32 v162, v98, v162
	v_mul_f32_e32 v163, v99, v163
	v_mul_f32_e32 v164, v88, v164
	v_mul_f32_e32 v165, v89, v165
	v_mul_f32_e32 v166, v90, v166
	v_mul_f32_e32 v167, v91, v167
	v_mul_f32_e32 v160, v160, v92
	v_mul_f32_e32 v161, v161, v93
	v_mul_f32_e32 v162, v162, v94
	v_mul_f32_e32 v163, v163, v95
	v_mul_f32_e32 v164, v164, v84
	v_mul_f32_e32 v165, v165, v85
	v_mul_f32_e32 v166, v166, v86
	v_mul_f32_e32 v167, v167, v87
	v_cvt_pk_bf16_f32 v176, v160, v161
	v_cvt_pk_bf16_f32 v177, v162, v163
	v_cvt_pk_bf16_f32 v178, v164, v165
	v_cvt_pk_bf16_f32 v179, v166, v167
	global_store_dwordx4 v[184:185], v[176:179], off
	v_mul_f32_e32 v160, 0xbfb8aa3b, v80
	v_mul_f32_e32 v161, 0xbfb8aa3b, v81
	v_mul_f32_e32 v162, 0xbfb8aa3b, v82
	v_mul_f32_e32 v163, 0xbfb8aa3b, v83
	v_mul_f32_e32 v164, 0xbfb8aa3b, v72
	v_mul_f32_e32 v165, 0xbfb8aa3b, v73
	v_mul_f32_e32 v166, 0xbfb8aa3b, v74
	v_mul_f32_e32 v167, 0xbfb8aa3b, v75
	s_mov_b64 s[24:25], 0x42000
	v_exp_f32_e32 v160, v160
	v_exp_f32_e32 v161, v161
	v_exp_f32_e32 v162, v162
	v_exp_f32_e32 v163, v163
	v_exp_f32_e32 v164, v164
	v_exp_f32_e32 v165, v165
	v_exp_f32_e32 v166, v166
	v_exp_f32_e32 v167, v167
	v_lshl_add_u64 v[186:187], v[152:153], 0, s[24:25]
	v_add_f32_e32 v160, 1.0, v160
	v_add_f32_e32 v161, 1.0, v161
	v_add_f32_e32 v162, 1.0, v162
	v_add_f32_e32 v163, 1.0, v163
	v_add_f32_e32 v164, 1.0, v164
	v_add_f32_e32 v165, 1.0, v165
	v_add_f32_e32 v166, 1.0, v166
	v_add_f32_e32 v167, 1.0, v167
	v_rcp_f32_e32 v160, v160
	v_rcp_f32_e32 v161, v161
	v_rcp_f32_e32 v162, v162
	v_rcp_f32_e32 v163, v163
	v_rcp_f32_e32 v164, v164
	v_rcp_f32_e32 v165, v165
	v_rcp_f32_e32 v166, v166
	v_rcp_f32_e32 v167, v167
	v_mul_f32_e32 v160, v80, v160
	v_mul_f32_e32 v161, v81, v161
	v_mul_f32_e32 v162, v82, v162
	v_mul_f32_e32 v163, v83, v163
	v_mul_f32_e32 v164, v72, v164
	v_mul_f32_e32 v165, v73, v165
	v_mul_f32_e32 v166, v74, v166
	v_mul_f32_e32 v167, v75, v167
	v_mul_f32_e32 v160, v160, v76
	v_mul_f32_e32 v161, v161, v77
	v_mul_f32_e32 v162, v162, v78
	v_mul_f32_e32 v163, v163, v79
	v_mul_f32_e32 v164, v164, v68
	v_mul_f32_e32 v165, v165, v69
	v_mul_f32_e32 v166, v166, v70
	v_mul_f32_e32 v167, v167, v71
	v_cvt_pk_bf16_f32 v180, v160, v161
	v_cvt_pk_bf16_f32 v181, v162, v163
	v_cvt_pk_bf16_f32 v182, v164, v165
	v_cvt_pk_bf16_f32 v183, v166, v167
	global_store_dwordx4 v[186:187], v[180:183], off
	v_mul_f32_e32 v160, 0xbfb8aa3b, v64
	v_mul_f32_e32 v161, 0xbfb8aa3b, v65
	v_mul_f32_e32 v162, 0xbfb8aa3b, v66
	v_mul_f32_e32 v163, 0xbfb8aa3b, v67
	v_mul_f32_e32 v164, 0xbfb8aa3b, v56
	v_mul_f32_e32 v165, 0xbfb8aa3b, v57
	v_mul_f32_e32 v166, 0xbfb8aa3b, v58
	v_mul_f32_e32 v167, 0xbfb8aa3b, v59
	s_mov_b64 s[24:25], 0xb0000
	v_exp_f32_e32 v160, v160
	v_exp_f32_e32 v161, v161
	v_exp_f32_e32 v162, v162
	v_exp_f32_e32 v163, v163
	v_exp_f32_e32 v164, v164
	v_exp_f32_e32 v165, v165
	v_exp_f32_e32 v166, v166
	v_exp_f32_e32 v167, v167
	v_lshl_add_u64 v[184:185], v[152:153], 0, s[24:25]
	v_add_f32_e32 v160, 1.0, v160
	v_add_f32_e32 v161, 1.0, v161
	v_add_f32_e32 v162, 1.0, v162
	v_add_f32_e32 v163, 1.0, v163
	v_add_f32_e32 v164, 1.0, v164
	v_add_f32_e32 v165, 1.0, v165
	v_add_f32_e32 v166, 1.0, v166
	v_add_f32_e32 v167, 1.0, v167
	v_rcp_f32_e32 v160, v160
	v_rcp_f32_e32 v161, v161
	v_rcp_f32_e32 v162, v162
	v_rcp_f32_e32 v163, v163
	v_rcp_f32_e32 v164, v164
	v_rcp_f32_e32 v165, v165
	v_rcp_f32_e32 v166, v166
	v_rcp_f32_e32 v167, v167
	v_mul_f32_e32 v160, v64, v160
	v_mul_f32_e32 v161, v65, v161
	v_mul_f32_e32 v162, v66, v162
	v_mul_f32_e32 v163, v67, v163
	v_mul_f32_e32 v164, v56, v164
	v_mul_f32_e32 v165, v57, v165
	v_mul_f32_e32 v166, v58, v166
	v_mul_f32_e32 v167, v59, v167
	v_mul_f32_e32 v160, v160, v60
	v_mul_f32_e32 v161, v161, v61
	v_mul_f32_e32 v162, v162, v62
	v_mul_f32_e32 v163, v163, v63
	v_mul_f32_e32 v164, v164, v52
	v_mul_f32_e32 v165, v165, v53
	v_mul_f32_e32 v166, v166, v54
	v_mul_f32_e32 v167, v167, v55
	v_cvt_pk_bf16_f32 v176, v160, v161
	v_cvt_pk_bf16_f32 v177, v162, v163
	v_cvt_pk_bf16_f32 v178, v164, v165
	v_cvt_pk_bf16_f32 v179, v166, v167
	global_store_dwordx4 v[184:185], v[176:179], off
	v_mul_f32_e32 v160, 0xbfb8aa3b, v48
	v_mul_f32_e32 v161, 0xbfb8aa3b, v49
	v_mul_f32_e32 v162, 0xbfb8aa3b, v50
	v_mul_f32_e32 v163, 0xbfb8aa3b, v51
	v_mul_f32_e32 v164, 0xbfb8aa3b, v40
	v_mul_f32_e32 v165, 0xbfb8aa3b, v41
	v_mul_f32_e32 v166, 0xbfb8aa3b, v42
	v_mul_f32_e32 v167, 0xbfb8aa3b, v43
	s_mov_b64 s[24:25], 0xc6000
	v_exp_f32_e32 v160, v160
	v_exp_f32_e32 v161, v161
	v_exp_f32_e32 v162, v162
	v_exp_f32_e32 v163, v163
	v_exp_f32_e32 v164, v164
	v_exp_f32_e32 v165, v165
	v_exp_f32_e32 v166, v166
	v_exp_f32_e32 v167, v167
	v_lshl_add_u64 v[186:187], v[152:153], 0, s[24:25]
	v_add_f32_e32 v160, 1.0, v160
	v_add_f32_e32 v161, 1.0, v161
	v_add_f32_e32 v162, 1.0, v162
	v_add_f32_e32 v163, 1.0, v163
	v_add_f32_e32 v164, 1.0, v164
	v_add_f32_e32 v165, 1.0, v165
	v_add_f32_e32 v166, 1.0, v166
	v_add_f32_e32 v167, 1.0, v167
	v_rcp_f32_e32 v160, v160
	v_rcp_f32_e32 v161, v161
	v_rcp_f32_e32 v162, v162
	v_rcp_f32_e32 v163, v163
	v_rcp_f32_e32 v164, v164
	v_rcp_f32_e32 v165, v165
	v_rcp_f32_e32 v166, v166
	v_rcp_f32_e32 v167, v167
	v_mul_f32_e32 v160, v48, v160
	v_mul_f32_e32 v161, v49, v161
	v_mul_f32_e32 v162, v50, v162
	v_mul_f32_e32 v163, v51, v163
	v_mul_f32_e32 v164, v40, v164
	v_mul_f32_e32 v165, v41, v165
	v_mul_f32_e32 v166, v42, v166
	v_mul_f32_e32 v167, v43, v167
	v_mul_f32_e32 v160, v160, v44
	v_mul_f32_e32 v161, v161, v45
	v_mul_f32_e32 v162, v162, v46
	v_mul_f32_e32 v163, v163, v47
	v_mul_f32_e32 v164, v164, v36
	v_mul_f32_e32 v165, v165, v37
	v_mul_f32_e32 v166, v166, v38
	v_mul_f32_e32 v167, v167, v39
	v_cvt_pk_bf16_f32 v180, v160, v161
	v_cvt_pk_bf16_f32 v181, v162, v163
	v_cvt_pk_bf16_f32 v182, v164, v165
	v_cvt_pk_bf16_f32 v183, v166, v167
	global_store_dwordx4 v[186:187], v[180:183], off
	v_mul_f32_e32 v160, 0xbfb8aa3b, v32
	v_mul_f32_e32 v161, 0xbfb8aa3b, v33
	v_mul_f32_e32 v162, 0xbfb8aa3b, v34
	v_mul_f32_e32 v163, 0xbfb8aa3b, v35
	v_mul_f32_e32 v164, 0xbfb8aa3b, v24
	v_mul_f32_e32 v165, 0xbfb8aa3b, v25
	v_mul_f32_e32 v166, 0xbfb8aa3b, v26
	v_mul_f32_e32 v167, 0xbfb8aa3b, v27
	s_mov_b64 s[24:25], 0xdc000
	v_exp_f32_e32 v160, v160
	v_exp_f32_e32 v161, v161
	v_exp_f32_e32 v162, v162
	v_exp_f32_e32 v163, v163
	v_exp_f32_e32 v164, v164
	v_exp_f32_e32 v165, v165
	v_exp_f32_e32 v166, v166
	v_exp_f32_e32 v167, v167
	v_lshl_add_u64 v[184:185], v[152:153], 0, s[24:25]
	v_add_f32_e32 v160, 1.0, v160
	v_add_f32_e32 v161, 1.0, v161
	v_add_f32_e32 v162, 1.0, v162
	v_add_f32_e32 v163, 1.0, v163
	v_add_f32_e32 v164, 1.0, v164
	v_add_f32_e32 v165, 1.0, v165
	v_add_f32_e32 v166, 1.0, v166
	v_add_f32_e32 v167, 1.0, v167
	v_rcp_f32_e32 v160, v160
	v_rcp_f32_e32 v161, v161
	v_rcp_f32_e32 v162, v162
	v_rcp_f32_e32 v163, v163
	v_rcp_f32_e32 v164, v164
	v_rcp_f32_e32 v165, v165
	v_rcp_f32_e32 v166, v166
	v_rcp_f32_e32 v167, v167
	v_mul_f32_e32 v160, v32, v160
	v_mul_f32_e32 v161, v33, v161
	v_mul_f32_e32 v162, v34, v162
	v_mul_f32_e32 v163, v35, v163
	v_mul_f32_e32 v164, v24, v164
	v_mul_f32_e32 v165, v25, v165
	v_mul_f32_e32 v166, v26, v166
	v_mul_f32_e32 v167, v27, v167
	v_mul_f32_e32 v160, v160, v28
	v_mul_f32_e32 v161, v161, v29
	v_mul_f32_e32 v162, v162, v30
	v_mul_f32_e32 v163, v163, v31
	v_mul_f32_e32 v164, v164, v20
	v_mul_f32_e32 v165, v165, v21
	v_mul_f32_e32 v166, v166, v22
	v_mul_f32_e32 v167, v167, v23
	v_cvt_pk_bf16_f32 v176, v160, v161
	v_cvt_pk_bf16_f32 v177, v162, v163
	v_cvt_pk_bf16_f32 v178, v164, v165
	v_cvt_pk_bf16_f32 v179, v166, v167
	global_store_dwordx4 v[184:185], v[176:179], off
	v_mul_f32_e32 v160, 0xbfb8aa3b, v16
	v_mul_f32_e32 v161, 0xbfb8aa3b, v17
	v_mul_f32_e32 v162, 0xbfb8aa3b, v18
	v_mul_f32_e32 v163, 0xbfb8aa3b, v19
	v_mul_f32_e32 v164, 0xbfb8aa3b, v8
	v_mul_f32_e32 v165, 0xbfb8aa3b, v9
	v_mul_f32_e32 v166, 0xbfb8aa3b, v10
	v_mul_f32_e32 v167, 0xbfb8aa3b, v11
	s_mov_b64 s[24:25], 0xf2000
	v_exp_f32_e32 v160, v160
	v_exp_f32_e32 v161, v161
	v_exp_f32_e32 v162, v162
	v_exp_f32_e32 v163, v163
	v_exp_f32_e32 v164, v164
	v_exp_f32_e32 v165, v165
	v_exp_f32_e32 v166, v166
	v_exp_f32_e32 v167, v167
	v_lshl_add_u64 v[186:187], v[152:153], 0, s[24:25]
	v_add_f32_e32 v160, 1.0, v160
	v_add_f32_e32 v161, 1.0, v161
	v_add_f32_e32 v162, 1.0, v162
	v_add_f32_e32 v163, 1.0, v163
	v_add_f32_e32 v164, 1.0, v164
	v_add_f32_e32 v165, 1.0, v165
	v_add_f32_e32 v166, 1.0, v166
	v_add_f32_e32 v167, 1.0, v167
	v_rcp_f32_e32 v160, v160
	v_rcp_f32_e32 v161, v161
	v_rcp_f32_e32 v162, v162
	v_rcp_f32_e32 v163, v163
	v_rcp_f32_e32 v164, v164
	v_rcp_f32_e32 v165, v165
	v_rcp_f32_e32 v166, v166
	v_rcp_f32_e32 v167, v167
	v_mul_f32_e32 v160, v16, v160
	v_mul_f32_e32 v161, v17, v161
	v_mul_f32_e32 v162, v18, v162
	v_mul_f32_e32 v163, v19, v163
	v_mul_f32_e32 v164, v8, v164
	v_mul_f32_e32 v165, v9, v165
	v_mul_f32_e32 v166, v10, v166
	v_mul_f32_e32 v167, v11, v167
	v_mul_f32_e32 v160, v160, v12
	v_mul_f32_e32 v161, v161, v13
	v_mul_f32_e32 v162, v162, v14
	v_mul_f32_e32 v163, v163, v15
	v_mul_f32_e32 v164, v164, v4
	v_mul_f32_e32 v165, v165, v5
	v_mul_f32_e32 v166, v166, v6
	v_mul_f32_e32 v167, v167, v7
	v_cvt_pk_bf16_f32 v180, v160, v161
	v_cvt_pk_bf16_f32 v181, v162, v163
	v_cvt_pk_bf16_f32 v182, v164, v165
	v_cvt_pk_bf16_f32 v183, v166, v167
	global_store_dwordx4 v[186:187], v[180:183], off
	s_mov_b64 s[24:25], -1
	s_cbranch_vccnz .LBB0_1567
	s_andn2_b64 vcc, exec, s[10:11]
	s_cbranch_vccnz .LBB0_1566
	s_barrier
	s_branch .LBB0_1566
